# N and UC phases: counted waits that let the previous token's stores stay outstanding
# baseline (speedup 1.0000x reference)
; DI unsigned pk2(float lo, float hi) { const f32x2 v = {lo, hi}; return __builtin_bit_cast(unsigned, __builtin_convertvector(v, bf16v2)); }
; DI void phase_rms_bf16(const float* X, const float* g, bf16_t* XN) {
;     ...
;     for (int m = gw; m < M; m += NGW) {
;         const f32x4* xr = (const f32x4*)(X + (size_t)m * D);
;         f32x4 v[8]; float s = 0.f;
; #pragma unroll
;         for (int j = 0; j < 8; ++j) { v[j] = xr[lane + 64 * j]; s += (v[j].x * v[j].x + v[j].y * v[j].y) + (v[j].z * v[j].z + v[j].w * v[j].w); }
;         const float rstd = rsqrtf(wave_sum(s) * (1.f / D) + 1e-6f);
;         u32x2* o8 = (u32x2*)(XN + (size_t)m * D);
; #pragma unroll
;         for (int j = 0; j < 8; ++j) { const f32x4 y = v[j] * rstd * gv[j]; u32x2 w; w.x = pk2(y.x, y.y); w.y = pk2(y.z, y.w); o8[lane + 64 * j] = w; }
;     }
; DI void phase_rms_final(float* X, const float* g) {
;     ...
;     for (int m = gw; m < M; m += NGW) {
;         f32x4* xr = (f32x4*)(X + (size_t)m * D);
;         f32x4 v[8]; float s = 0.f;
; #pragma unroll
;         for (int j = 0; j < 8; ++j) { v[j] = xr[lane + 64 * j]; s += (v[j].x * v[j].x + v[j].y * v[j].y) + (v[j].z * v[j].z + v[j].w * v[j].w); }
;         const float rstd = rsqrtf(wave_sum(s) * (1.f / D) + 1e-6f);
; #pragma unroll
;         for (int j = 0; j < 8; ++j) xr[lane + 64 * j] = v[j] * rstd * gv[j];
.Lpn_common:
	v_readlane_b32 s1, v252, 0
	v_lshrrev_b32_e32 v5, 6, v185
	v_and_b32_e32 v6, 63, v185
	v_lshlrev_b32_e32 v0, 4, v6
	v_lshlrev_b32_e32 v1, 3, v6
	v_or_b32_e32 v7, 0x1000, v0
	v_readfirstlane_b32 s44, v5
	s_lshl_b32 s45, s1, 3
	s_add_u32 s45, s45, s44
	s_cmp_eq_u32 s19, 0
	s_cselect_b32 s22, s78, s94
	s_cselect_b32 s23, s79, s95
	s_cselect_b32 s46, 0x2000, 0
	s_add_u32 s22, s22, s46
	s_addc_u32 s23, s23, 0
	global_load_dwordx4 v[64:67], v0, s[22:23]
	global_load_dwordx4 v[68:71], v0, s[22:23] offset:1024
	global_load_dwordx4 v[72:75], v0, s[22:23] offset:2048
	global_load_dwordx4 v[76:79], v0, s[22:23] offset:3072
	global_load_dwordx4 v[80:83], v7, s[22:23]
	global_load_dwordx4 v[84:87], v7, s[22:23] offset:1024
	global_load_dwordx4 v[88:91], v7, s[22:23] offset:2048
	global_load_dwordx4 v[92:95], v7, s[22:23] offset:3072
	s_lshl_b32 s46, s45, 13
	s_add_u32 s38, s96, s46
	s_addc_u32 s39, s97, 0
	s_mov_b64 s[42:43], s[38:39]
	s_lshl_b32 s46, s45, 12
	s_add_u32 s40, s20, s46
	s_addc_u32 s41, s21, 0
	s_mov_b32 s101, 0x3a000000
	s_mov_b32 s100, 0x1000000
	s_mov_b32 s0, 0
	global_load_dwordx4 v[8:11], v0, s[38:39]
	global_load_dwordx4 v[12:15], v0, s[38:39] offset:1024
	global_load_dwordx4 v[16:19], v0, s[38:39] offset:2048
	global_load_dwordx4 v[20:23], v0, s[38:39] offset:3072
	global_load_dwordx4 v[24:27], v7, s[38:39]
	global_load_dwordx4 v[28:31], v7, s[38:39] offset:1024
	global_load_dwordx4 v[32:35], v7, s[38:39] offset:2048
	global_load_dwordx4 v[36:39], v7, s[38:39] offset:3072
	s_waitcnt vmcnt(0)
.Lpn_loop:
	s_add_u32 s38, s38, s100
	s_addc_u32 s39, s39, 0
	global_load_dwordx4 v[96:99], v0, s[38:39]
	global_load_dwordx4 v[100:103], v0, s[38:39] offset:1024
	global_load_dwordx4 v[104:107], v0, s[38:39] offset:2048
	global_load_dwordx4 v[108:111], v0, s[38:39] offset:3072
	global_load_dwordx4 v[112:115], v7, s[38:39]
	global_load_dwordx4 v[116:119], v7, s[38:39] offset:1024
	global_load_dwordx4 v[120:123], v7, s[38:39] offset:2048
	global_load_dwordx4 v[124:127], v7, s[38:39] offset:3072
	s_waitcnt vmcnt(16)
	v_pk_mul_f32 v[40:41], v[8:9], v[8:9]
	v_pk_mul_f32 v[42:43], v[10:11], v[10:11]
	v_pk_fma_f32 v[40:41], v[12:13], v[12:13], v[40:41]
	v_pk_fma_f32 v[42:43], v[14:15], v[14:15], v[42:43]
	v_pk_fma_f32 v[40:41], v[16:17], v[16:17], v[40:41]
	v_pk_fma_f32 v[42:43], v[18:19], v[18:19], v[42:43]
	v_pk_fma_f32 v[40:41], v[20:21], v[20:21], v[40:41]
	v_pk_fma_f32 v[42:43], v[22:23], v[22:23], v[42:43]
	v_pk_fma_f32 v[40:41], v[24:25], v[24:25], v[40:41]
	v_pk_fma_f32 v[42:43], v[26:27], v[26:27], v[42:43]
	v_pk_fma_f32 v[40:41], v[28:29], v[28:29], v[40:41]
	v_pk_fma_f32 v[42:43], v[30:31], v[30:31], v[42:43]
	v_pk_fma_f32 v[40:41], v[32:33], v[32:33], v[40:41]
	v_pk_fma_f32 v[42:43], v[34:35], v[34:35], v[42:43]
	v_pk_fma_f32 v[40:41], v[36:37], v[36:37], v[40:41]
	v_pk_fma_f32 v[42:43], v[38:39], v[38:39], v[42:43]
	v_pk_add_f32 v[40:41], v[40:41], v[42:43]
	s_nop 0
	v_add_f32_e32 v44, v40, v41
	s_nop 1
	v_add_f32_dpp v44, v44, v44 quad_perm:[1,0,3,2] row_mask:0xf bank_mask:0xf
	s_nop 1
	v_add_f32_dpp v44, v44, v44 quad_perm:[2,3,0,1] row_mask:0xf bank_mask:0xf
	s_nop 1
	v_add_f32_dpp v44, v44, v44 row_half_mirror row_mask:0xf bank_mask:0xf
	s_nop 1
	v_add_f32_dpp v44, v44, v44 row_mirror row_mask:0xf bank_mask:0xf
	s_nop 1
	v_readlane_b32 s44, v44, 0
	v_readlane_b32 s45, v44, 16
	v_readlane_b32 s46, v44, 32
	v_readlane_b32 s47, v44, 48
	s_nop 1
	v_mov_b32_e32 v46, s44
	v_add_f32_e32 v46, s45, v46
	v_add_f32_e32 v46, s46, v46
	v_add_f32_e32 v46, s47, v46
	v_fma_f32 v46, v46, s101, v190
	v_rsq_f32_e32 v46, v46
	s_nop 0
	v_pk_mul_f32 v[8:9], v[8:9], v[46:47] op_sel_hi:[1,0]
	v_pk_mul_f32 v[10:11], v[10:11], v[46:47] op_sel_hi:[1,0]
	v_pk_mul_f32 v[12:13], v[12:13], v[46:47] op_sel_hi:[1,0]
	v_pk_mul_f32 v[14:15], v[14:15], v[46:47] op_sel_hi:[1,0]
	v_pk_mul_f32 v[16:17], v[16:17], v[46:47] op_sel_hi:[1,0]
	v_pk_mul_f32 v[18:19], v[18:19], v[46:47] op_sel_hi:[1,0]
	v_pk_mul_f32 v[20:21], v[20:21], v[46:47] op_sel_hi:[1,0]
	v_pk_mul_f32 v[22:23], v[22:23], v[46:47] op_sel_hi:[1,0]
	v_pk_mul_f32 v[24:25], v[24:25], v[46:47] op_sel_hi:[1,0]
	v_pk_mul_f32 v[26:27], v[26:27], v[46:47] op_sel_hi:[1,0]
	v_pk_mul_f32 v[28:29], v[28:29], v[46:47] op_sel_hi:[1,0]
	v_pk_mul_f32 v[30:31], v[30:31], v[46:47] op_sel_hi:[1,0]
	v_pk_mul_f32 v[32:33], v[32:33], v[46:47] op_sel_hi:[1,0]
	v_pk_mul_f32 v[34:35], v[34:35], v[46:47] op_sel_hi:[1,0]
	v_pk_mul_f32 v[36:37], v[36:37], v[46:47] op_sel_hi:[1,0]
	v_pk_mul_f32 v[38:39], v[38:39], v[46:47] op_sel_hi:[1,0]
	v_pk_mul_f32 v[8:9], v[8:9], v[64:65]
	v_pk_mul_f32 v[10:11], v[10:11], v[66:67]
	v_pk_mul_f32 v[12:13], v[12:13], v[68:69]
	v_pk_mul_f32 v[14:15], v[14:15], v[70:71]
	v_pk_mul_f32 v[16:17], v[16:17], v[72:73]
	v_pk_mul_f32 v[18:19], v[18:19], v[74:75]
	v_pk_mul_f32 v[20:21], v[20:21], v[76:77]
	v_pk_mul_f32 v[22:23], v[22:23], v[78:79]
	v_pk_mul_f32 v[24:25], v[24:25], v[80:81]
	v_pk_mul_f32 v[26:27], v[26:27], v[82:83]
	v_pk_mul_f32 v[28:29], v[28:29], v[84:85]
	v_pk_mul_f32 v[30:31], v[30:31], v[86:87]
	v_pk_mul_f32 v[32:33], v[32:33], v[88:89]
	v_pk_mul_f32 v[34:35], v[34:35], v[90:91]
	v_pk_mul_f32 v[36:37], v[36:37], v[92:93]
	v_pk_mul_f32 v[38:39], v[38:39], v[94:95]
	s_cmp_eq_u32 s19, 0
	s_cbranch_scc0 .Lpn_t0_f32
	v_cvt_pk_bf16_f32 v48, v8, v9
	v_cvt_pk_bf16_f32 v49, v10, v11
	v_cvt_pk_bf16_f32 v50, v12, v13
	v_cvt_pk_bf16_f32 v51, v14, v15
	v_cvt_pk_bf16_f32 v52, v16, v17
	v_cvt_pk_bf16_f32 v53, v18, v19
	v_cvt_pk_bf16_f32 v54, v20, v21
	v_cvt_pk_bf16_f32 v55, v22, v23
	v_cvt_pk_bf16_f32 v56, v24, v25
	v_cvt_pk_bf16_f32 v57, v26, v27
	v_cvt_pk_bf16_f32 v58, v28, v29
	v_cvt_pk_bf16_f32 v59, v30, v31
	v_cvt_pk_bf16_f32 v60, v32, v33
	v_cvt_pk_bf16_f32 v61, v34, v35
	v_cvt_pk_bf16_f32 v62, v36, v37
	v_cvt_pk_bf16_f32 v63, v38, v39
	global_store_dwordx2 v1, v[48:49], s[40:41]
	global_store_dwordx2 v1, v[50:51], s[40:41] offset:512
	global_store_dwordx2 v1, v[52:53], s[40:41] offset:1024
	global_store_dwordx2 v1, v[54:55], s[40:41] offset:1536
	global_store_dwordx2 v1, v[56:57], s[40:41] offset:2048
	global_store_dwordx2 v1, v[58:59], s[40:41] offset:2560
	global_store_dwordx2 v1, v[60:61], s[40:41] offset:3072
	global_store_dwordx2 v1, v[62:63], s[40:41] offset:3584
	s_branch .Lpn_t0_done

; DI unsigned pk2(float lo, float hi) { const f32x2 v = {lo, hi}; return __builtin_bit_cast(unsigned, __builtin_convertvector(v, bf16v2)); }
; DI void phase_rms_bf16(const float* X, const float* g, bf16_t* XN) {
;     ...
;     for (int m = gw; m < M; m += NGW) {
;         const f32x4* xr = (const f32x4*)(X + (size_t)m * D);
;         f32x4 v[8]; float s = 0.f;
; #pragma unroll
;         for (int j = 0; j < 8; ++j) { v[j] = xr[lane + 64 * j]; s += (v[j].x * v[j].x + v[j].y * v[j].y) + (v[j].z * v[j].z + v[j].w * v[j].w); }
;         const float rstd = rsqrtf(wave_sum(s) * (1.f / D) + 1e-6f);
;         u32x2* o8 = (u32x2*)(XN + (size_t)m * D);
; #pragma unroll
;         for (int j = 0; j < 8; ++j) { const f32x4 y = v[j] * rstd * gv[j]; u32x2 w; w.x = pk2(y.x, y.y); w.y = pk2(y.z, y.w); o8[lane + 64 * j] = w; }
;     }
; DI void phase_rms_final(float* X, const float* g) {
;     ...
;     for (int m = gw; m < M; m += NGW) {
;         f32x4* xr = (f32x4*)(X + (size_t)m * D);
;         f32x4 v[8]; float s = 0.f;
; #pragma unroll
;         for (int j = 0; j < 8; ++j) { v[j] = xr[lane + 64 * j]; s += (v[j].x * v[j].x + v[j].y * v[j].y) + (v[j].z * v[j].z + v[j].w * v[j].w); }
;         const float rstd = rsqrtf(wave_sum(s) * (1.f / D) + 1e-6f);
; #pragma unroll
;         for (int j = 0; j < 8; ++j) xr[lane + 64 * j] = v[j] * rstd * gv[j];
.Lpn_t0_done:
	s_add_u32 s40, s40, 0x800000
	s_addc_u32 s41, s41, 0
	s_add_u32 s42, s42, 0x1000000
	s_addc_u32 s43, s43, 0
	s_cmp_eq_u32 s0, 7
	s_cselect_b32 s100, 0, s100
	s_add_u32 s38, s38, s100
	s_addc_u32 s39, s39, 0
	global_load_dwordx4 v[8:11], v0, s[38:39]
	global_load_dwordx4 v[12:15], v0, s[38:39] offset:1024
	global_load_dwordx4 v[16:19], v0, s[38:39] offset:2048
	global_load_dwordx4 v[20:23], v0, s[38:39] offset:3072
	global_load_dwordx4 v[24:27], v7, s[38:39]
	global_load_dwordx4 v[28:31], v7, s[38:39] offset:1024
	global_load_dwordx4 v[32:35], v7, s[38:39] offset:2048
	global_load_dwordx4 v[36:39], v7, s[38:39] offset:3072
	s_waitcnt vmcnt(16)
	v_pk_mul_f32 v[40:41], v[96:97], v[96:97]
	v_pk_mul_f32 v[42:43], v[98:99], v[98:99]
	v_pk_fma_f32 v[40:41], v[100:101], v[100:101], v[40:41]
	v_pk_fma_f32 v[42:43], v[102:103], v[102:103], v[42:43]
	v_pk_fma_f32 v[40:41], v[104:105], v[104:105], v[40:41]
	v_pk_fma_f32 v[42:43], v[106:107], v[106:107], v[42:43]
	v_pk_fma_f32 v[40:41], v[108:109], v[108:109], v[40:41]
	v_pk_fma_f32 v[42:43], v[110:111], v[110:111], v[42:43]
	v_pk_fma_f32 v[40:41], v[112:113], v[112:113], v[40:41]
	v_pk_fma_f32 v[42:43], v[114:115], v[114:115], v[42:43]
	v_pk_fma_f32 v[40:41], v[116:117], v[116:117], v[40:41]
	v_pk_fma_f32 v[42:43], v[118:119], v[118:119], v[42:43]
	v_pk_fma_f32 v[40:41], v[120:121], v[120:121], v[40:41]
	v_pk_fma_f32 v[42:43], v[122:123], v[122:123], v[42:43]
	v_pk_fma_f32 v[40:41], v[124:125], v[124:125], v[40:41]
	v_pk_fma_f32 v[42:43], v[126:127], v[126:127], v[42:43]
	v_pk_add_f32 v[40:41], v[40:41], v[42:43]
	s_nop 0
	v_add_f32_e32 v44, v40, v41
	s_nop 1
	v_add_f32_dpp v44, v44, v44 quad_perm:[1,0,3,2] row_mask:0xf bank_mask:0xf
	s_nop 1
	v_add_f32_dpp v44, v44, v44 quad_perm:[2,3,0,1] row_mask:0xf bank_mask:0xf
	s_nop 1
	v_add_f32_dpp v44, v44, v44 row_half_mirror row_mask:0xf bank_mask:0xf
	s_nop 1
	v_add_f32_dpp v44, v44, v44 row_mirror row_mask:0xf bank_mask:0xf
	s_nop 1
	v_readlane_b32 s44, v44, 0
	v_readlane_b32 s45, v44, 16
	v_readlane_b32 s46, v44, 32
	v_readlane_b32 s47, v44, 48
	s_nop 1
	v_mov_b32_e32 v46, s44
	v_add_f32_e32 v46, s45, v46
	v_add_f32_e32 v46, s46, v46
	v_add_f32_e32 v46, s47, v46
	v_fma_f32 v46, v46, s101, v190
	v_rsq_f32_e32 v46, v46
	s_nop 0
	v_pk_mul_f32 v[96:97], v[96:97], v[46:47] op_sel_hi:[1,0]
	v_pk_mul_f32 v[98:99], v[98:99], v[46:47] op_sel_hi:[1,0]
	v_pk_mul_f32 v[100:101], v[100:101], v[46:47] op_sel_hi:[1,0]
	v_pk_mul_f32 v[102:103], v[102:103], v[46:47] op_sel_hi:[1,0]
	v_pk_mul_f32 v[104:105], v[104:105], v[46:47] op_sel_hi:[1,0]
	v_pk_mul_f32 v[106:107], v[106:107], v[46:47] op_sel_hi:[1,0]
	v_pk_mul_f32 v[108:109], v[108:109], v[46:47] op_sel_hi:[1,0]
	v_pk_mul_f32 v[110:111], v[110:111], v[46:47] op_sel_hi:[1,0]
	v_pk_mul_f32 v[112:113], v[112:113], v[46:47] op_sel_hi:[1,0]
	v_pk_mul_f32 v[114:115], v[114:115], v[46:47] op_sel_hi:[1,0]
	v_pk_mul_f32 v[116:117], v[116:117], v[46:47] op_sel_hi:[1,0]
	v_pk_mul_f32 v[118:119], v[118:119], v[46:47] op_sel_hi:[1,0]
	v_pk_mul_f32 v[120:121], v[120:121], v[46:47] op_sel_hi:[1,0]
	v_pk_mul_f32 v[122:123], v[122:123], v[46:47] op_sel_hi:[1,0]
	v_pk_mul_f32 v[124:125], v[124:125], v[46:47] op_sel_hi:[1,0]
	v_pk_mul_f32 v[126:127], v[126:127], v[46:47] op_sel_hi:[1,0]
	v_pk_mul_f32 v[96:97], v[96:97], v[64:65]
	v_pk_mul_f32 v[98:99], v[98:99], v[66:67]
	v_pk_mul_f32 v[100:101], v[100:101], v[68:69]
	v_pk_mul_f32 v[102:103], v[102:103], v[70:71]
	v_pk_mul_f32 v[104:105], v[104:105], v[72:73]
	v_pk_mul_f32 v[106:107], v[106:107], v[74:75]
	v_pk_mul_f32 v[108:109], v[108:109], v[76:77]
	v_pk_mul_f32 v[110:111], v[110:111], v[78:79]
	v_pk_mul_f32 v[112:113], v[112:113], v[80:81]
	v_pk_mul_f32 v[114:115], v[114:115], v[82:83]
	v_pk_mul_f32 v[116:117], v[116:117], v[84:85]
	v_pk_mul_f32 v[118:119], v[118:119], v[86:87]
	v_pk_mul_f32 v[120:121], v[120:121], v[88:89]
	v_pk_mul_f32 v[122:123], v[122:123], v[90:91]
	v_pk_mul_f32 v[124:125], v[124:125], v[92:93]
	v_pk_mul_f32 v[126:127], v[126:127], v[94:95]
	s_cmp_eq_u32 s19, 0
	s_cbranch_scc0 .Lpn_t1_f32
	v_cvt_pk_bf16_f32 v48, v96, v97
	v_cvt_pk_bf16_f32 v49, v98, v99
	v_cvt_pk_bf16_f32 v50, v100, v101
	v_cvt_pk_bf16_f32 v51, v102, v103
	v_cvt_pk_bf16_f32 v52, v104, v105
	v_cvt_pk_bf16_f32 v53, v106, v107
	v_cvt_pk_bf16_f32 v54, v108, v109
	v_cvt_pk_bf16_f32 v55, v110, v111
	v_cvt_pk_bf16_f32 v56, v112, v113
	v_cvt_pk_bf16_f32 v57, v114, v115
	v_cvt_pk_bf16_f32 v58, v116, v117
	v_cvt_pk_bf16_f32 v59, v118, v119
	v_cvt_pk_bf16_f32 v60, v120, v121
	v_cvt_pk_bf16_f32 v61, v122, v123
	v_cvt_pk_bf16_f32 v62, v124, v125
	v_cvt_pk_bf16_f32 v63, v126, v127
	global_store_dwordx2 v1, v[48:49], s[40:41]
	global_store_dwordx2 v1, v[50:51], s[40:41] offset:512
	global_store_dwordx2 v1, v[52:53], s[40:41] offset:1024
	global_store_dwordx2 v1, v[54:55], s[40:41] offset:1536
	global_store_dwordx2 v1, v[56:57], s[40:41] offset:2048
	global_store_dwordx2 v1, v[58:59], s[40:41] offset:2560
	global_store_dwordx2 v1, v[60:61], s[40:41] offset:3072
	global_store_dwordx2 v1, v[62:63], s[40:41] offset:3584
	s_branch .Lpn_t1_done

; DI void phase_peer_u(const Args& a, int layer, int ci) {
;     ...
;             const int mn = m + NGW < M ? m + NGW : m;
;             const int idAn = IDX[(size_t)mn * 128 + lane], idBn = IDX[(size_t)mn * 128 + 64 + lane];
;             const u32x4 xan = *(const u32x4*)(XN + (size_t)mn * D), xbn = *(const u32x4*)(XN + (size_t)mn * D + 8);
;             float glA = 0.f, glB = 0.f, pdA = 0.f, pdB = 0.f, rstdu = 0.f;
;             if (ci == 1) {
;                 glA = GATE[(size_t)m * 128 + lane] * GSUM[(size_t)m * 8 + (lane >> 4)] * (1.f / V_SCALE);
;                 glB = GATE[(size_t)m * 128 + 64 + lane] * GSUM[(size_t)m * 8 + 4 + (lane >> 4)] * (1.f / V_SCALE);
;                 pdA = PD[(size_t)m * 128 + lane]; pdB = PD[(size_t)m * 128 + 64 + lane];
;                 rstdu = __builtin_bit_cast(float, __builtin_amdgcn_readfirstlane(__builtin_bit_cast(int, rsqrtf(wave_sum(lane < 32 ? ((const float*)(ws + WS_RSS))[((size_t)layer * M + m) * 32 + lane] : 0.f) * (1.f / D) + 1e-6f) * (1.f / U_SCALE))));
.Lpuc_entry:
	v_readlane_b32 s1, v252, 0
	v_readlane_b32 s19, v255, 12
	v_lshrrev_b32_e32 v5, 6, v185
	v_and_b32_e32 v6, 63, v185
	v_lshlrev_b32_e32 v0, 2, v6
	v_and_b32_e32 v1, 31, v6
	v_lshlrev_b32_e32 v1, 2, v1
	v_lshrrev_b32_e32 v3, 5, v6
	v_bfe_u32 v4, v6, 1, 1
	v_lshl_or_b32 v3, v3, 1, v4
	v_bfe_u32 v7, v6, 2, 3
	v_and_b32_e32 v4, 1, v6
	v_lshl_or_b32 v2, v3, 4, v7
	v_lshl_or_b32 v2, v4, 3, v2
	v_lshlrev_b32_e32 v2, 2, v2
	v_lshlrev_b32_e32 v3, 2, v3
	v_readfirstlane_b32 s44, v5
	s_lshl_b32 s45, s1, 3
	s_add_u32 s45, s45, s44
	s_lshl_b32 s46, s45, 13
	s_add_u32 s46, s46, 0x20000000
	s_add_u32 s38, s98, s46
	s_addc_u32 s39, s99, 0
	s_lshl_b32 s46, s45, 13
	s_add_u32 s46, s46, 0x7000000
	s_add_u32 s42, s98, s46
	s_addc_u32 s43, s99, 0
	s_mov_b64 s[16:17], s[42:43]
	s_lshl_b32 s46, s19, 22
	s_lshl_b32 s47, s45, 11
	s_add_u32 s46, s46, s47
	s_add_u32 s46, s46, 0xd800000
	s_add_u32 s40, s98, s46
	s_addc_u32 s41, s99, 0
	s_lshl_b32 s46, s45, 9
	s_add_u32 s46, s46, 0x5e00000
	s_add_u32 s24, s98, s46
	s_addc_u32 s25, s99, 0
	s_mov_b32 s101, 0x39800000
	s_mov_b32 s19, 0x3d372713
	s_mov_b32 s100, 0x200
	s_mov_b32 s0, 0
	s_add_u32 s22, s38, 0x1000000
	s_addc_u32 s23, s39, 0
	global_load_dword v8, v0, s[22:23]
	global_load_dword v9, v0, s[22:23] offset:256
	s_add_u32 s22, s22, 0x2000000
	s_addc_u32 s23, s23, 0
	global_load_dword v10, v0, s[22:23]
	global_load_dword v11, v0, s[22:23] offset:256
	s_add_u32 s22, s22, 0x2000000
	s_addc_u32 s23, s23, 0
	global_load_dword v12, v0, s[22:23]
	global_load_dword v13, v0, s[22:23] offset:256
	s_add_u32 s22, s22, 0x2000000
	s_addc_u32 s23, s23, 0
	global_load_dword v14, v0, s[22:23]
	global_load_dword v15, v0, s[22:23] offset:256
	s_add_u32 s22, s22, 0x2000000
	s_addc_u32 s23, s23, 0
	global_load_dword v16, v0, s[22:23]
	global_load_dword v17, v0, s[22:23] offset:256
	s_add_u32 s22, s22, 0x2000000
	s_addc_u32 s23, s23, 0
	global_load_dword v18, v0, s[22:23]
	global_load_dword v19, v0, s[22:23] offset:256
	s_add_u32 s22, s22, 0x2000000
	s_addc_u32 s23, s23, 0
	global_load_dword v20, v0, s[22:23]
	global_load_dword v21, v0, s[22:23] offset:256
	s_add_u32 s22, s22, 0x2000000
	s_addc_u32 s23, s23, 0
	global_load_dword v22, v0, s[22:23]
	global_load_dword v23, v0, s[22:23] offset:256
	global_load_dword v40, v1, s[40:41]
	global_load_dword v41, v2, s[42:43]
	global_load_dword v42, v2, s[42:43] offset:256
	global_load_dword v43, v3, s[24:25]
	global_load_dword v44, v3, s[24:25] offset:16
	s_waitcnt vmcnt(0)
.Lpuc_loop:
	s_add_u32 s38, s38, s100
	s_addc_u32 s39, s39, 0
	s_lshr_b32 s44, s100, 2
	s_add_u32 s40, s40, s44
	s_addc_u32 s41, s41, 0
	s_lshr_b32 s44, s100, 4
	s_add_u32 s24, s24, s44
	s_addc_u32 s25, s25, 0
	s_add_u32 s42, s42, s100
	s_addc_u32 s43, s43, 0
	s_add_u32 s22, s38, 0x1000000
	s_addc_u32 s23, s39, 0
	global_load_dword v56, v0, s[22:23]
	global_load_dword v57, v0, s[22:23] offset:256
	s_add_u32 s22, s22, 0x2000000
	s_addc_u32 s23, s23, 0
	global_load_dword v58, v0, s[22:23]
	global_load_dword v59, v0, s[22:23] offset:256
	s_add_u32 s22, s22, 0x2000000
	s_addc_u32 s23, s23, 0
	global_load_dword v60, v0, s[22:23]
	global_load_dword v61, v0, s[22:23] offset:256
	s_add_u32 s22, s22, 0x2000000
	s_addc_u32 s23, s23, 0
	global_load_dword v62, v0, s[22:23]
	global_load_dword v63, v0, s[22:23] offset:256
	s_add_u32 s22, s22, 0x2000000
	s_addc_u32 s23, s23, 0
	global_load_dword v64, v0, s[22:23]
	global_load_dword v65, v0, s[22:23] offset:256
	s_add_u32 s22, s22, 0x2000000
	s_addc_u32 s23, s23, 0
	global_load_dword v66, v0, s[22:23]
	global_load_dword v67, v0, s[22:23] offset:256
	s_add_u32 s22, s22, 0x2000000
	s_addc_u32 s23, s23, 0
	global_load_dword v68, v0, s[22:23]
	global_load_dword v69, v0, s[22:23] offset:256
	s_add_u32 s22, s22, 0x2000000
	s_addc_u32 s23, s23, 0
	global_load_dword v70, v0, s[22:23]
	global_load_dword v71, v0, s[22:23] offset:256
	global_load_dword v88, v1, s[40:41]
	global_load_dword v89, v2, s[42:43]
	global_load_dword v90, v2, s[42:43] offset:256
	global_load_dword v91, v3, s[24:25]
	global_load_dword v92, v3, s[24:25] offset:16
	s_waitcnt vmcnt(23)
; DI void phase_peer_u(const Args& a, int layer, int ci) {
;     ...
;             if (ci == 1) {
;                 glA = GATE[(size_t)m * 128 + lane] * GSUM[(size_t)m * 8 + (lane >> 4)] * (1.f / V_SCALE);
;                 glB = GATE[(size_t)m * 128 + 64 + lane] * GSUM[(size_t)m * 8 + 4 + (lane >> 4)] * (1.f / V_SCALE);
;                 pdA = PD[(size_t)m * 128 + lane]; pdB = PD[(size_t)m * 128 + 64 + lane];
;                 rstdu = __builtin_bit_cast(float, __builtin_amdgcn_readfirstlane(__builtin_bit_cast(int, rsqrtf(wave_sum(lane < 32 ? ((const float*)(ws + WS_RSS))[((size_t)layer * M + m) * 32 + lane] : 0.f) * (1.f / D) + 1e-6f) * (1.f / U_SCALE))));
;             }
;             float rA = 0.f, rB = 0.f;
; #pragma unroll 1
;             for (int g8 = 0; g8 < 16; ++g8) {
;                 u32x4 nxt[8];
;                 if (g8 < 15) gat_loadhu(U, idA, idB, g8 + 1, lo16, nxt); else gat_loadhu(U, idAn, idBn, 0, lo16, nxt);
;                 const float c0 = dots4h(xa, xb, cur[0], cur[1], cur[2], cur[3], lane);
;                 const float c1 = dots4h(xa, xb, cur[4], cur[5], cur[6], cur[7], lane);
;                 const int q4 = (g8 & 7) * 2;
;                 const float cv = (lane >> 2) == q4 ? c0 : c1;
;                 const bool mine = (lane >> 3) == (g8 & 7);
;                 if (ci == 0) { if (g8 < 8) rA = mine ? cv : rA; else rB = mine ? cv : rB; }
;                 else { if (g8 < 8) rA = mine ? gelu_tanh((cv + pdA) * rstdu) * glA : rA; else rB = mine ? gelu_tanh((cv + pdB) * rstdu) * glB : rB; }
; #pragma unroll
;                 for (int j = 0; j < 8; ++j) cur[j] = nxt[j];
;             }
;             if (ci == 0) { PD[(size_t)m * 128 + lane] = rA; PD[(size_t)m * 128 + 64 + lane] = rB; }
;             else { GATE[(size_t)m * 128 + lane] = rA; GATE[(size_t)m * 128 + 64 + lane] = rB; }
	v_add_f32_e32 v104, v8, v10
	v_add_f32_e32 v104, v104, v12
	v_add_f32_e32 v104, v104, v14
	v_add_f32_e32 v104, v104, v16
	v_add_f32_e32 v104, v104, v18
	v_add_f32_e32 v104, v104, v20
	v_add_f32_e32 v104, v104, v22
	v_add_f32_e32 v105, v9, v11
	v_add_f32_e32 v105, v105, v13
	v_add_f32_e32 v105, v105, v15
	v_add_f32_e32 v105, v105, v17
	v_add_f32_e32 v105, v105, v19
	v_add_f32_e32 v105, v105, v21
	v_add_f32_e32 v105, v105, v23
	v_mov_b32_e32 v106, v40
	s_nop 1
	v_add_f32_dpp v106, v106, v106 quad_perm:[1,0,3,2] row_mask:0xf bank_mask:0xf
	s_nop 1
	v_add_f32_dpp v106, v106, v106 quad_perm:[2,3,0,1] row_mask:0xf bank_mask:0xf
	s_nop 1
	v_add_f32_dpp v106, v106, v106 row_half_mirror row_mask:0xf bank_mask:0xf
	s_nop 1
	v_add_f32_dpp v106, v106, v106 row_mirror row_mask:0xf bank_mask:0xf
	s_nop 1
	v_readlane_b32 s44, v106, 0
	v_readlane_b32 s45, v106, 16
	v_readlane_b32 s46, v106, 32
	v_readlane_b32 s47, v106, 48
	s_nop 1
	v_mov_b32_e32 v107, s44
	v_add_f32_e32 v107, s45, v107
	v_add_f32_e32 v107, s46, v107
	v_add_f32_e32 v107, s47, v107
	v_fma_f32 v107, v107, s101, v190
	v_rsq_f32_e32 v107, v107
	s_nop 0
	v_mul_f32_e32 v107, 0x3b000000, v107
	v_mul_f32_e32 v108, 0x3c800000, v43
	v_mul_f32_e32 v109, 0x3c800000, v44
	v_mul_f32_e32 v108, v108, v41
	v_mul_f32_e32 v109, v109, v42
	v_mul_f32_e32 v104, v104, v107
	v_mul_f32_e32 v110, v104, v104
	v_mul_f32_e32 v110, v110, v104
	v_fma_f32 v110, v110, s19, v104
	v_mul_f32_e32 v110, 0x40135761, v110
	v_exp_f32_e32 v110, v110
	s_nop 0
	v_add_f32_e32 v110, 1.0, v110
	v_rcp_f32_e32 v110, v110
	s_nop 0
	v_fma_f32 v111, -v104, v110, v104
	v_mul_f32_e32 v111, v111, v108
	v_mul_f32_e32 v105, v105, v107
	v_mul_f32_e32 v112, v105, v105
	v_mul_f32_e32 v112, v112, v105
	v_fma_f32 v112, v112, s19, v105
	v_mul_f32_e32 v112, 0x40135761, v112
	v_exp_f32_e32 v112, v112
	s_nop 0
	v_add_f32_e32 v112, 1.0, v112
	v_rcp_f32_e32 v112, v112
	s_nop 0
	v_fma_f32 v113, -v105, v112, v105
	v_mul_f32_e32 v113, v113, v109
	global_store_dword v2, v111, s[16:17]
	global_store_dword v2, v113, s[16:17] offset:256
	s_add_u32 s16, s16, 0x200
	s_addc_u32 s17, s17, 0
	s_cmp_eq_u32 s0, 7
	s_cselect_b32 s100, 0, s100
	s_add_u32 s38, s38, s100
	s_addc_u32 s39, s39, 0
	s_lshr_b32 s44, s100, 2
	s_add_u32 s40, s40, s44
	s_addc_u32 s41, s41, 0
	s_lshr_b32 s44, s100, 4
	s_add_u32 s24, s24, s44
	s_addc_u32 s25, s25, 0
	s_add_u32 s42, s42, s100
	s_addc_u32 s43, s43, 0
	s_add_u32 s22, s38, 0x1000000
	s_addc_u32 s23, s39, 0
	global_load_dword v8, v0, s[22:23]
	global_load_dword v9, v0, s[22:23] offset:256
	s_add_u32 s22, s22, 0x2000000
	s_addc_u32 s23, s23, 0
	global_load_dword v10, v0, s[22:23]
	global_load_dword v11, v0, s[22:23] offset:256
	s_add_u32 s22, s22, 0x2000000
	s_addc_u32 s23, s23, 0
	global_load_dword v12, v0, s[22:23]
	global_load_dword v13, v0, s[22:23] offset:256
	s_add_u32 s22, s22, 0x2000000
	s_addc_u32 s23, s23, 0
	global_load_dword v14, v0, s[22:23]
	global_load_dword v15, v0, s[22:23] offset:256
	s_add_u32 s22, s22, 0x2000000
	s_addc_u32 s23, s23, 0
	global_load_dword v16, v0, s[22:23]
	global_load_dword v17, v0, s[22:23] offset:256
	s_add_u32 s22, s22, 0x2000000
	s_addc_u32 s23, s23, 0
	global_load_dword v18, v0, s[22:23]
	global_load_dword v19, v0, s[22:23] offset:256
	s_add_u32 s22, s22, 0x2000000
	s_addc_u32 s23, s23, 0
	global_load_dword v20, v0, s[22:23]
	global_load_dword v21, v0, s[22:23] offset:256
	s_add_u32 s22, s22, 0x2000000
	s_addc_u32 s23, s23, 0
	global_load_dword v22, v0, s[22:23]
	global_load_dword v23, v0, s[22:23] offset:256
	global_load_dword v40, v1, s[40:41]
	global_load_dword v41, v2, s[42:43]
	global_load_dword v42, v2, s[42:43] offset:256
	global_load_dword v43, v3, s[24:25]
	global_load_dword v44, v3, s[24:25] offset:16
	s_waitcnt vmcnt(23)
	v_add_f32_e32 v104, v56, v58
	v_add_f32_e32 v104, v104, v60
	v_add_f32_e32 v104, v104, v62
	v_add_f32_e32 v104, v104, v64
	v_add_f32_e32 v104, v104, v66
	v_add_f32_e32 v104, v104, v68
	v_add_f32_e32 v104, v104, v70
	v_add_f32_e32 v105, v57, v59
	v_add_f32_e32 v105, v105, v61
	v_add_f32_e32 v105, v105, v63
	v_add_f32_e32 v105, v105, v65
	v_add_f32_e32 v105, v105, v67
	v_add_f32_e32 v105, v105, v69
	v_add_f32_e32 v105, v105, v71
	v_mov_b32_e32 v106, v88
	s_nop 1
	v_add_f32_dpp v106, v106, v106 quad_perm:[1,0,3,2] row_mask:0xf bank_mask:0xf
	s_nop 1
	v_add_f32_dpp v106, v106, v106 quad_perm:[2,3,0,1] row_mask:0xf bank_mask:0xf
	s_nop 1
	v_add_f32_dpp v106, v106, v106 row_half_mirror row_mask:0xf bank_mask:0xf
	s_nop 1
	v_add_f32_dpp v106, v106, v106 row_mirror row_mask:0xf bank_mask:0xf
	s_nop 1
	v_readlane_b32 s44, v106, 0
	v_readlane_b32 s45, v106, 16
	v_readlane_b32 s46, v106, 32
	v_readlane_b32 s47, v106, 48
	s_nop 1
	v_mov_b32_e32 v107, s44
	v_add_f32_e32 v107, s45, v107
	v_add_f32_e32 v107, s46, v107
	v_add_f32_e32 v107, s47, v107
	v_fma_f32 v107, v107, s101, v190
	v_rsq_f32_e32 v107, v107
	s_nop 0
	v_mul_f32_e32 v107, 0x3b000000, v107
	v_mul_f32_e32 v108, 0x3c800000, v91
	v_mul_f32_e32 v109, 0x3c800000, v92
	v_mul_f32_e32 v108, v108, v89
	v_mul_f32_e32 v109, v109, v90
	v_mul_f32_e32 v104, v104, v107
	v_mul_f32_e32 v110, v104, v104
	v_mul_f32_e32 v110, v110, v104
	v_fma_f32 v110, v110, s19, v104
	v_mul_f32_e32 v110, 0x40135761, v110
	v_exp_f32_e32 v110, v110
	s_nop 0
	v_add_f32_e32 v110, 1.0, v110
	v_rcp_f32_e32 v110, v110
	s_nop 0
	v_fma_f32 v111, -v104, v110, v104
	v_mul_f32_e32 v111, v111, v108
	v_mul_f32_e32 v105, v105, v107
	v_mul_f32_e32 v112, v105, v105
	v_mul_f32_e32 v112, v112, v105
	v_fma_f32 v112, v112, s19, v105
	v_mul_f32_e32 v112, 0x40135761, v112
	v_exp_f32_e32 v112, v112
	s_nop 0
	v_add_f32_e32 v112, 1.0, v112
	v_rcp_f32_e32 v112, v112
	s_nop 0
	v_fma_f32 v113, -v105, v112, v105
	v_mul_f32_e32 v113, v113, v109
	global_store_dword v2, v111, s[16:17]
	global_store_dword v2, v113, s[16:17] offset:256
	s_add_u32 s16, s16, 0x200
	s_addc_u32 s17, s17, 0
	s_add_u32 s0, s0, 1
	s_cmp_lt_u32 s0, 8
	s_cbranch_scc1 .Lpuc_loop
	s_waitcnt vmcnt(0)
	s_branch .LBB0_495
